# v94 + phase-0 row loop: 64-lane sum of squares via DPP quad_perm/row_mirror + permlane swaps instead of a 6-hop ds_bpermute butterfly
# speedup vs baseline: 1.0010x; 1.0010x over previous
.LBB0_66:
	s_or_b64 exec, exec, s[16:17]
	v_lshlrev_b64 v[40:41], 11, v[20:21]
	v_lshl_add_u64 v[22:23], v[22:23], 0, v[18:19]
	v_lshl_add_u64 v[52:53], v[12:13], 0, v[40:41]
	global_load_dwordx4 v[36:39], v[22:23], off
	global_load_dwordx4 v[40:43], v[22:23], off offset:1024
	global_load_dwordx4 v[44:47], v[22:23], off offset:2048
	global_load_dwordx4 v[48:51], v[22:23], off offset:3072
	s_waitcnt vmcnt(3)
	v_cvt_pk_bf16_f32 v128, v36, v37
	v_cvt_pk_bf16_f32 v129, v38, v39
	v_mul_f32_e32 v4, v37, v37
	global_store_dwordx2 v[52:53], v[128:129], off
	v_fmac_f32_e32 v4, v36, v36
	v_fmac_f32_e32 v4, v38, v38
	v_fmac_f32_e32 v4, v39, v39
	s_waitcnt vmcnt(3)
	v_cvt_pk_bf16_f32 v130, v40, v41
	v_cvt_pk_bf16_f32 v131, v42, v43
	v_mul_f32_e32 v22, v41, v41
	global_store_dwordx2 v[52:53], v[130:131], off offset:512
	v_fmac_f32_e32 v22, v40, v40
	v_fmac_f32_e32 v22, v42, v42
	v_fmac_f32_e32 v22, v43, v43
	v_add_f32_e32 v4, v4, v22
	s_waitcnt vmcnt(3)
	v_cvt_pk_bf16_f32 v132, v44, v45
	v_cvt_pk_bf16_f32 v133, v46, v47
	v_mul_f32_e32 v22, v45, v45
	global_store_dwordx2 v[52:53], v[132:133], off offset:1024
	v_fmac_f32_e32 v22, v44, v44
	v_fmac_f32_e32 v22, v46, v46
	v_fmac_f32_e32 v22, v47, v47
	v_add_f32_e32 v4, v4, v22
	s_waitcnt vmcnt(3)
	v_mul_f32_e32 v22, v49, v49
	v_fmac_f32_e32 v22, v48, v48
	v_fmac_f32_e32 v22, v50, v50
	v_fmac_f32_e32 v22, v51, v51
	v_add_f32_e32 v4, v4, v22
	s_nop 1
	v_add_f32_dpp v4, v4, v4 quad_perm:[1,0,3,2] row_mask:0xf bank_mask:0xf
	v_cvt_pk_bf16_f32 v134, v48, v49
	v_cvt_pk_bf16_f32 v135, v50, v51
	global_store_dwordx2 v[52:53], v[134:135], off offset:1536
	s_nop 1
	v_add_f32_dpp v4, v4, v4 quad_perm:[2,3,0,1] row_mask:0xf bank_mask:0xf
	s_nop 1
	v_add_f32_dpp v4, v4, v4 row_half_mirror row_mask:0xf bank_mask:0xf
	s_nop 1
	v_add_f32_dpp v4, v4, v4 row_mirror row_mask:0xf bank_mask:0xf
	v_mov_b32_e32 v22, v4
	s_nop 1
	v_permlane16_swap_b32_e32 v4, v22
	v_add_f32_e32 v4, v4, v22
	v_mov_b32_e32 v22, v4
	s_nop 1
	v_permlane32_swap_b32_e32 v4, v22
	s_and_saveexec_b64 s[16:17], s[0:1]
	s_cbranch_execz .LBB0_63
	v_readlane_b32 s20, v254, 52
	v_readlane_b32 s21, v254, 53
	s_waitcnt lgkmcnt(0)
	v_add_f32_e32 v4, v4, v22
	v_lshl_add_u64 v[20:21], v[20:21], 2, s[20:21]
	v_add_co_u32_e32 v22, vcc, 0x40000, v20
	global_store_dword v[20:21], v4, off
	s_nop 0
	v_addc_co_u32_e32 v23, vcc, 0, v21, vcc
	global_store_dword v[22:23], v5, off
	v_add_co_u32_e32 v22, vcc, 0x80000, v20
	s_nop 1
	v_addc_co_u32_e32 v23, vcc, 0, v21, vcc
	v_add_co_u32_e32 v20, vcc, 0xc0000, v20
	global_store_dword v[22:23], v5, off
	s_nop 0
	v_addc_co_u32_e32 v21, vcc, 0, v21, vcc
	global_store_dword v[20:21], v5, off
	s_branch .LBB0_63
